# scan roles: producers on waves 2-5, weight-conversion workers on waves 6,7 (consumers share SIMDs with producers)
# speedup vs baseline: 1.0366x; 1.0044x over previous
.LBB0_147:
	s_or_b64 exec, exec, s[4:5]
	v_ashrrev_i32_e32 v0, 6, v1
	v_and_b32_e32 v122, 63, v29
	v_cmp_gt_i32_e32 vcc, 6, v0
	s_waitcnt lgkmcnt(0)
	s_barrier
	s_and_saveexec_b64 s[4:5], vcc
	s_xor_b64 s[66:67], exec, s[4:5]
	s_cbranch_execz .LBB0_179
	v_cmp_gt_i32_e32 vcc, 8, v0
	s_mov_b64 s[4:5], exec
	v_writelane_b32 v244, s4, 40
	s_and_b64 s[8:9], s[4:5], vcc
	s_nop 0
	v_writelane_b32 v244, s5, 41
	s_mov_b64 exec, s[8:9]
	s_cbranch_execz .LBB0_178
	v_bfe_u32 v1, v1, 6, 1
	v_mul_lo_u32 v2, v1, s6
	v_readlane_b32 s8, v246, 0
	v_readlane_b32 s9, v246, 1
	s_nop 0
	v_add_u32_e32 v79, s8, v2
	v_cmp_gt_i32_e32 vcc, s75, v79
	s_and_b64 exec, exec, vcc
	s_cbranch_execz .LBB0_178
	s_mov_b32 s8, 0xf300
	v_mad_u32_u24 v87, v1, s8, 0
	v_lshlrev_b32_e32 v1, 5, v1
	s_add_i32 s8, 0, 0x20a00
	v_add_u32_e32 v123, s8, v1
	v_readlane_b32 s8, v246, 25
	v_lshlrev_b32_e32 v2, 9, v122
	v_lshrrev_b32_e32 v78, 4, v122
	v_add_u32_e32 v1, s8, v1
	v_and_b32_e32 v127, 0x7800, v2
	v_and_b32_e32 v3, 15, v29
	v_lshrrev_b32_e32 v1, 4, v1
	v_readlane_b32 s8, v246, 26
	v_lshlrev_b32_e32 v86, 11, v78
	v_lshlrev_b32_e32 v4, 2, v127
	v_mov_b32_e32 v5, v28
	v_add_u32_e32 v124, s8, v1
	v_cmp_gt_i32_e32 vcc, 2, v0
	v_lshlrev_b32_e32 v0, 4, v3
	v_mov_b32_e32 v1, v28
	v_and_b32_e32 v2, 3, v29
	v_lshl_add_u64 v[88:89], s[62:63], 0, v[4:5]
	v_or_b32_e32 v4, 0x2000, v86
	v_or_b32_e32 v6, 0x4000, v86
	v_or_b32_e32 v8, 0x6000, v86
	v_lshlrev_b32_e32 v125, 2, v3
	v_cmp_eq_u32_e64 s[8:9], 0, v122
	v_cmp_eq_u32_e64 s[10:11], 15, v3
	v_lshlrev_b32_e32 v126, 11, v3
	v_lshl_add_u64 v[80:81], s[12:13], 0, v[0:1]
	v_lshl_add_u64 v[82:83], s[14:15], 0, v[0:1]
	v_lshl_add_u64 v[84:85], s[16:17], 0, v[0:1]
	v_cmp_eq_u32_e64 s[12:13], 0, v3
	v_cmp_eq_u32_e64 s[14:15], 1, v3
	v_cmp_eq_u32_e64 s[16:17], 2, v3
	v_cmp_eq_u32_e64 s[18:19], 3, v3
	v_cmp_eq_u32_e64 s[20:21], 4, v3
	v_cmp_eq_u32_e64 s[22:23], 5, v3
	v_cmp_eq_u32_e64 s[24:25], 6, v3
	v_cmp_eq_u32_e64 s[26:27], 7, v3
	v_cmp_eq_u32_e64 s[28:29], 8, v3
	v_cmp_eq_u32_e64 s[30:31], 9, v3
	v_cmp_eq_u32_e64 s[34:35], 10, v3
	v_cmp_eq_u32_e64 s[36:37], 11, v3
	v_cmp_eq_u32_e64 s[38:39], 12, v3
	v_cmp_eq_u32_e64 s[40:41], 13, v3
	v_cmp_eq_u32_e64 s[42:43], 14, v3
	v_lshl_add_u64 v[90:91], s[68:69], 0, v[0:1]
	v_lshl_add_u64 v[92:93], s[2:3], 0, v[0:1]
	v_lshl_add_u64 v[94:95], s[44:45], 0, v[0:1]
	v_lshl_add_u64 v[96:97], s[0:1], 0, v[0:1]
	v_mul_u32_u24_e32 v128, 0x500, v78
	s_mov_b64 s[68:69], 0
	v_lshlrev_b32_e32 v98, 2, v78
	v_lshlrev_b32_e32 v100, 2, v4
	v_lshlrev_b32_e32 v102, 2, v6
	v_lshlrev_b32_e32 v104, 2, v8
	v_lshlrev_b32_e32 v106, 2, v2
	v_mov_b32_e32 v129, v79
	s_branch .LBB0_152
